# v6 with scheduler LDS latency model 260 cycles (K-fragment reads hoisted earlier)
# baseline (speedup 1.0000x reference)
; template <int NPE>
; DI void qkt_r(f32x16& p0, f32x16& p1, const char* Ks, const char* Ps, const bf16x8* qr, int r32, int hi) {
;   p0 = f32x16{}; p1 = f32x16{};
; #pragma unroll
;   for (int d0 = 0; d0 < 8; ++d0) { int cb = (d0 * 16 + hi * 8) * 2;
;     bf16x8 b0 = *reinterpret_cast<const bf16x8*>(Ks + KSWZ(r32, cb));
;     bf16x8 b1 = *reinterpret_cast<const bf16x8*>(Ks + KSWZ(32 + r32, cb));
;     p0 = __builtin_amdgcn_mfma_f32_32x32x16_bf16(b0, qr[d0], p0, 0, 0, 0);
;     p1 = __builtin_amdgcn_mfma_f32_32x32x16_bf16(b1, qr[d0], p1, 0, 0, 0); }
; #pragma unroll
;   for (int d0 = 0; d0 < NPE; ++d0) { int cb = (d0 * 16 + hi * 8) * 2;
;     bf16x8 b0 = *reinterpret_cast<const bf16x8*>(Ps + PSWZ(r32, cb));
;     bf16x8 b1 = *reinterpret_cast<const bf16x8*>(Ps + PSWZ(32 + r32, cb));
;     p0 = __builtin_amdgcn_mfma_f32_32x32x16_bf16(b0, qr[8 + d0], p0, 0, 0, 0);
;     p1 = __builtin_amdgcn_mfma_f32_32x32x16_bf16(b1, qr[8 + d0], p1, 0, 0, 0); }
.LBB0_928:
	s_mov_b32 s63, s1
	v_exp_f32_e32 v160, v185
	v_add_u32_e32 v68, s63, v188
	v_add_u32_e32 v243, s63, v191
	ds_read_b128 v[64:67], v68 offset:16384
	ds_read_b128 v[244:247], v243 offset:16384
	v_add_u32_e32 v252, s63, v194
	v_add_u32_e32 v253, s63, v197
	ds_read_b128 v[226:229], v252 offset:16384
	v_add_u32_e32 v144, s63, v200
	ds_read_b128 v[68:71], v68 offset:24576
	ds_read_b128 v[248:251], v243 offset:24576
	v_add_u32_e32 v243, s63, v203
	ds_read_b128 v[230:233], v252 offset:24576
	v_add_u32_e32 v252, s63, v205
	v_exp_f32_e32 v182, v182
	v_exp_f32_e32 v183, v183
	v_exp_f32_e32 v180, v180
	v_exp_f32_e32 v181, v181
	v_exp_f32_e32 v178, v178
	v_exp_f32_e32 v179, v179
	s_mov_b32 s1, s2
	v_exp_f32_e32 v185, v177
	v_cvt_pk_bf16_f32 v177, v162, v164
	v_exp_f32_e32 v215, v175
	v_cvt_pk_bf16_f32 v175, v166, v168
	v_exp_f32_e32 v186, v174
	v_exp_f32_e32 v216, v172
	v_exp_f32_e32 v225, v173
	v_cvt_pk_bf16_f32 v172, v219, v221
	v_cvt_pk_bf16_f32 v173, v217, v218
	v_cvt_pk_bf16_f32 v174, v167, v169
	v_permlane32_swap_b32_e32 v175, v177
	s_waitcnt lgkmcnt(5)
	v_mfma_f32_32x32x16_bf16 v[80:95], v[64:67], v[136:139], 0
	s_waitcnt lgkmcnt(4)
	v_mfma_f32_32x32x16_bf16 v[80:95], v[244:247], v[132:135], v[80:95]
	s_waitcnt lgkmcnt(3)
	v_mfma_f32_32x32x16_bf16 v[80:95], v[226:229], v[128:131], v[80:95]
	ds_read_b128 v[244:247], v253 offset:16384
	s_waitcnt lgkmcnt(3)
	v_mfma_f32_32x32x16_bf16 v[64:79], v[68:71], v[136:139], 0
	ds_read_b128 v[226:229], v144 offset:16384
	s_waitcnt lgkmcnt(3)
	v_mfma_f32_32x32x16_bf16 v[64:79], v[248:251], v[132:135], v[64:79]
	s_waitcnt lgkmcnt(2)
	v_mfma_f32_32x32x16_bf16 v[64:79], v[230:233], v[128:131], v[64:79]
	ds_read_b128 v[248:251], v253 offset:24576
	v_add_u32_e32 v253, s63, v206
	ds_read_b128 v[230:233], v144 offset:24576
	v_add_u32_e32 v144, s63, v207
	s_waitcnt lgkmcnt(3)
	v_mfma_f32_32x32x16_bf16 v[80:95], v[244:247], v[124:127], v[80:95]
	s_waitcnt lgkmcnt(2)
	v_mfma_f32_32x32x16_bf16 v[80:95], v[226:229], v[120:123], v[80:95]
	ds_read_b128 v[244:247], v243 offset:16384
	ds_read_b128 v[226:229], v252 offset:16384
	s_waitcnt lgkmcnt(3)
	v_mfma_f32_32x32x16_bf16 v[64:79], v[248:251], v[124:127], v[64:79]
	s_waitcnt lgkmcnt(2)
	v_mfma_f32_32x32x16_bf16 v[64:79], v[230:233], v[120:123], v[64:79]
	ds_read_b128 v[248:251], v243 offset:24576
	v_add_u32_e32 v243, s63, v208
	ds_read_b128 v[230:233], v252 offset:24576
	v_add_u32_e32 v252, s63, v209
	s_waitcnt lgkmcnt(3)
	v_mfma_f32_32x32x16_bf16 v[80:95], v[244:247], v[112:115], v[80:95]
	s_waitcnt lgkmcnt(2)
	v_mfma_f32_32x32x16_bf16 v[80:95], v[226:229], v[108:111], v[80:95]
	ds_read_b128 v[244:247], v253 offset:16384
	ds_read_b128 v[226:229], v144 offset:32768
	s_waitcnt lgkmcnt(3)
	v_mfma_f32_32x32x16_bf16 v[64:79], v[248:251], v[112:115], v[64:79]
	s_waitcnt lgkmcnt(2)
	v_mfma_f32_32x32x16_bf16 v[64:79], v[230:233], v[108:111], v[64:79]
	ds_read_b128 v[248:251], v253 offset:24576
	v_add_u32_e32 v253, s63, v210
	ds_read_b128 v[230:233], v144 offset:36864
	v_exp_f32_e32 v144, v184
	v_exp_f32_e32 v184, v176
	v_cvt_pk_bf16_f32 v176, v163, v165
	s_waitcnt lgkmcnt(3)
	v_mfma_f32_32x32x16_bf16 v[80:95], v[244:247], v[100:103], v[80:95]
	s_waitcnt lgkmcnt(2)
	v_mfma_f32_32x32x16_bf16 v[80:95], v[226:229], v[104:107], v[80:95]
	ds_read_b128 v[244:247], v243 offset:32768
	v_permlane32_swap_b32_e32 v174, v176
	ds_read_b128 v[226:229], v252 offset:32768
	s_waitcnt lgkmcnt(3)
	v_mfma_f32_32x32x16_bf16 v[64:79], v[248:251], v[100:103], v[64:79]
	s_waitcnt lgkmcnt(2)
	v_mfma_f32_32x32x16_bf16 v[64:79], v[230:233], v[104:107], v[64:79]
	ds_read_b128 v[248:251], v243 offset:36864
	v_add_u32_e32 v243, s1, v147
	ds_read_b128 v[230:233], v252 offset:36864
	s_waitcnt lgkmcnt(3)
	v_mfma_f32_32x32x16_bf16 v[80:95], v[244:247], v[140:143], v[80:95]
	s_waitcnt lgkmcnt(2)
	v_mfma_f32_32x32x16_bf16 v[80:95], v[226:229], v[96:99], v[80:95]
	ds_read_b128 v[244:247], v253 offset:32768
	v_exp_f32_e32 v226, v170
	v_add_f32_e32 v170, 0, v222
	v_exp_f32_e32 v227, v171
	v_add_f32_e32 v170, v224, v170
	v_cvt_pk_bf16_f32 v171, v220, v223
	v_add_f32_e32 v170, v220, v170
	s_waitcnt lgkmcnt(2)
	v_mfma_f32_32x32x16_bf16 v[64:79], v[248:251], v[140:143], v[64:79]
	v_add_f32_e32 v170, v223, v170
	v_permlane32_swap_b32_e32 v171, v173
	v_add_f32_e32 v170, v219, v170
	v_add_f32_e32 v170, v221, v170
	ds_read_b64_tr_b16 v[220:221], v243 offset:0x3000
	s_waitcnt lgkmcnt(2)
	v_mfma_f32_32x32x16_bf16 v[64:79], v[230:233], v[96:99], v[64:79]
	v_add_f32_e32 v170, v217, v170
	v_add_f32_e32 v170, v218, v170
	ds_read_b64_tr_b16 v[218:219], v243 offset:0x2800
	v_add_f32_e32 v170, v167, v170
	v_cvt_pk_bf16_f32 v167, v186, v215
	v_add_f32_e32 v170, v169, v170
	v_cvt_pk_bf16_f32 v169, v226, v227
	v_add_f32_e32 v170, v166, v170
	v_cvt_pk_bf16_f32 v166, v184, v185
	v_add_f32_e32 v170, v168, v170
	v_cvt_pk_bf16_f32 v168, v216, v225
	v_add_f32_e32 v170, v163, v170
	v_cvt_pk_bf16_f32 v163, v182, v183
	v_add_f32_e32 v170, v165, v170
	v_cvt_pk_bf16_f32 v165, v178, v179
	v_add_f32_e32 v170, v162, v170
	v_cvt_pk_bf16_f32 v162, v144, v160
	v_add_f32_e32 v170, v164, v170
	v_cvt_pk_bf16_f32 v164, v180, v181
	v_add_f32_e32 v170, v144, v170
	v_permlane32_swap_b32_e32 v163, v165
	v_add_f32_e32 v170, v160, v170
	v_permlane32_swap_b32_e32 v162, v164
	v_add_f32_e32 v170, v182, v170
	ds_read_b128 v[230:233], v253 offset:36864
	v_add_f32_e32 v170, v183, v170
	ds_read_b64_tr_b16 v[182:183], v243 offset:0x1000
	v_add_f32_e32 v170, v180, v170
	v_permlane32_swap_b32_e32 v166, v168
	v_add_f32_e32 v170, v181, v170
	ds_read_b64_tr_b16 v[180:181], v243 offset:0x800
	v_add_f32_e32 v170, v178, v170
	v_permlane32_swap_b32_e32 v167, v169
	v_add_f32_e32 v170, v179, v170
	ds_read_b64_tr_b16 v[178:179], v243 offset:0
	v_add_f32_e32 v170, v184, v170
	v_add_f32_e32 v170, v185, v170
	ds_read_b64_tr_b16 v[184:185], v243 offset:0x1800
	v_add_f32_e32 v170, v186, v170
	s_waitcnt lgkmcnt(7)
; #define SBAR() __builtin_amdgcn_sched_barrier(0)
; template <int OFF> DI s16x4 tr_read(int vb) {
;   s16x4 r; asm volatile("ds_read_b64_tr_b16 %0, %1 offset:%2" : "=&v"(r) : "v"(vb), "i"(OFF) : "memory"); return r;
; }
; template <int D0, bool SPLIT> DI void pv_one(f32x16& od, int vb, bf16x8 pa0, bf16x8 pa1, bf16x8 pa2, bf16x8 pa3) {
;     ...
;   if constexpr (SPLIT) {
;     { const s16x4 l0 = tr_read<v_rd_off(D0, 0, 0)>(vb), h0 = tr_read<v_rd_off(D0, 0, 1)>(vb), l1 = tr_read<v_rd_off(D0, 1, 0)>(vb), h1 = tr_read<v_rd_off(D0, 1, 1)>(vb);
;       asm volatile("s_waitcnt lgkmcnt(0)" ::: "memory"); SBAR();
;       od = __builtin_amdgcn_mfma_f32_32x32x16_bf16(PKV(l0, h0), pa0, od, 0, 0, 0);
;       od = __builtin_amdgcn_mfma_f32_32x32x16_bf16(PKV(l1, h1), pa1, od, 0, 0, 0); }
;     SBAR();
;     { const s16x4 l2 = tr_read<v_rd_off(D0, 2, 0)>(vb), h2 = tr_read<v_rd_off(D0, 2, 1)>(vb), l3 = tr_read<v_rd_off(D0, 3, 0)>(vb), h3 = tr_read<v_rd_off(D0, 3, 1)>(vb);
;       asm volatile("s_waitcnt lgkmcnt(0)" ::: "memory"); SBAR();
;       od = __builtin_amdgcn_mfma_f32_32x32x16_bf16(PKV(l2, h2), pa2, od, 0, 0, 0);
;       od = __builtin_amdgcn_mfma_f32_32x32x16_bf16(PKV(l3, h3), pa3, od, 0, 0, 0); }
;     SBAR();
;   } else {
;   const s16x4 l0 = tr_read<v_rd_off(D0, 0, 0)>(vb), h0 = tr_read<v_rd_off(D0, 0, 1)>(vb), l1 = tr_read<v_rd_off(D0, 1, 0)>(vb), h1 = tr_read<v_rd_off(D0, 1, 1)>(vb);
;   const s16x4 l2 = tr_read<v_rd_off(D0, 2, 0)>(vb), h2 = tr_read<v_rd_off(D0, 2, 1)>(vb), l3 = tr_read<v_rd_off(D0, 3, 0)>(vb), h3 = tr_read<v_rd_off(D0, 3, 1)>(vb);
;   asm volatile("s_waitcnt lgkmcnt(0)" ::: "memory"); SBAR();
;   od = __builtin_amdgcn_mfma_f32_32x32x16_bf16(PKV(l0, h0), pa0, od, 0, 0, 0);
;   od = __builtin_amdgcn_mfma_f32_32x32x16_bf16(PKV(l1, h1), pa1, od, 0, 0, 0);
;   od = __builtin_amdgcn_mfma_f32_32x32x16_bf16(PKV(l2, h2), pa2, od, 0, 0, 0);
;   od = __builtin_amdgcn_mfma_f32_32x32x16_bf16(PKV(l3, h3), pa3, od, 0, 0, 0);
;   }
; }
; template <bool SPLIT>
; DI void pv_d0(f32x16* o, int vb, bf16x8 pa0, bf16x8 pa1, bf16x8 pa2, bf16x8 pa3) {
;   pv_one<0, SPLIT>(o[0], vb, pa0, pa1, pa2, pa3); pv_one<1, SPLIT>(o[1], vb, pa0, pa1, pa2, pa3); pv_one<2, SPLIT>(o[2], vb, pa0, pa1, pa2, pa3); pv_one<3, SPLIT>(o[3], vb, pa0, pa1, pa2, pa3);
; }
	v_mfma_f32_32x32x16_bf16 v[80:95], v[244:247], v[116:119], v[80:95]
	v_add_f32_e32 v170, v215, v170
	v_add_f32_e32 v170, v216, v170
	ds_read_b64_tr_b16 v[216:217], v243 offset:0x2000
	v_add_f32_e32 v170, v225, v170
	v_add_f32_e32 v170, v226, v170
	v_add_f32_e32 v213, v227, v170
	v_cvt_pk_bf16_f32 v170, v222, v224
	ds_read_b64_tr_b16 v[222:223], v243 offset:0x3800
	ds_read_b64_tr_b16 v[224:225], v243 offset:0x3200
	ds_read_b64_tr_b16 v[226:227], v243 offset:0x3a00
	v_permlane32_swap_b32_e32 v170, v172
	v_mov_b32_e32 v214, v213
	v_max_f32_e32 v252, v81, v81
	v_max_f32_e32 v160, v80, v80
	v_permlane32_swap_b32_e32 v213, v214
	v_max_f32_e32 v252, v160, v252
	v_max3_f32 v252, v252, v82, v83
	v_max3_f32 v252, v252, v84, v85
	v_max3_f32 v252, v252, v86, v87
	v_max3_f32 v252, v252, v88, v89
	v_max3_f32 v252, v252, v90, v91
	v_max3_f32 v252, v252, v92, v93
	v_max3_f32 v252, v252, v94, v95
	s_waitcnt lgkmcnt(8)
	v_mfma_f32_32x32x16_bf16 v[64:79], v[230:233], v[116:119], v[64:79]
	s_waitcnt lgkmcnt(5)
	v_mfma_f32_32x32x16_bf16 v[16:31], v[178:181], v[170:173], v[16:31]
	s_waitcnt lgkmcnt(4)
	v_mfma_f32_32x32x16_bf16 v[16:31], v[182:185], v[174:177], v[16:31]
	ds_read_b64_tr_b16 v[178:179], v243 offset:0x200
	ds_read_b64_tr_b16 v[180:181], v243 offset:0xa00
	s_waitcnt lgkmcnt(5)
	v_mfma_f32_32x32x16_bf16 v[16:31], v[216:219], v[162:165], v[16:31]
	ds_read_b64_tr_b16 v[182:183], v243 offset:0x1200
	ds_read_b64_tr_b16 v[184:185], v243 offset:0x1a00
	s_waitcnt lgkmcnt(6)
	v_mfma_f32_32x32x16_bf16 v[16:31], v[220:223], v[166:169], v[16:31]
	ds_read_b64_tr_b16 v[216:217], v243 offset:0x2200
	ds_read_b64_tr_b16 v[218:219], v243 offset:0x2a00
	ds_read_b64_tr_b16 v[220:221], v243 offset:0x3400
	ds_read_b64_tr_b16 v[222:223], v243 offset:0x3c00
	v_max3_f32 v252, v252, v64, v65
	v_max3_f32 v252, v252, v66, v67
	v_max3_f32 v252, v252, v68, v69
	v_max3_f32 v252, v252, v70, v71
	v_max3_f32 v252, v252, v72, v73
	v_max3_f32 v252, v252, v74, v75
	v_max3_f32 v252, v252, v76, v77
	v_max3_f32 v252, v252, v78, v79
	v_mov_b32_e32 v160, v252
	s_waitcnt lgkmcnt(6)
	v_mfma_f32_32x32x16_bf16 v[48:63], v[178:181], v[170:173], v[48:63]
	s_waitcnt lgkmcnt(4)
	v_mfma_f32_32x32x16_bf16 v[48:63], v[182:185], v[174:177], v[48:63]
	ds_read_b64_tr_b16 v[178:179], v243 offset:0x400
	ds_read_b64_tr_b16 v[180:181], v243 offset:0xc00
	v_permlane32_swap_b32_e32 v252, v160
	v_max_f32_e32 v160, v160, v160
	v_max_f32_e32 v252, v252, v252
	s_waitcnt lgkmcnt(4)
	v_mfma_f32_32x32x16_bf16 v[48:63], v[216:219], v[162:165], v[48:63]
	ds_read_b64_tr_b16 v[182:183], v243 offset:0x1400
	ds_read_b64_tr_b16 v[184:185], v243 offset:0x1c00
	v_max_f32_e32 v252, v252, v160
	v_max_f32_e32 v160, v212, v212
	v_max_f32_e32 v160, v160, v252
	v_mfma_f32_32x32x16_bf16 v[48:63], v[224:227], v[166:169], v[48:63]
	ds_read_b64_tr_b16 v[216:217], v243 offset:0x2400
	ds_read_b64_tr_b16 v[218:219], v243 offset:0x2c00
	v_sub_f32_e32 v144, v212, v160
	v_mul_f32_e32 v144, 0x3dd53b94, v144
	ds_read_b64_tr_b16 v[224:225], v243 offset:0x3600
	ds_read_b64_tr_b16 v[226:227], v243 offset:0x3e00
	v_exp_f32_e32 v144, v144
	s_waitcnt lgkmcnt(6)
	v_mfma_f32_32x32x16_bf16 v[32:47], v[178:181], v[170:173], v[32:47]
	s_waitcnt lgkmcnt(4)
	v_mfma_f32_32x32x16_bf16 v[32:47], v[182:185], v[174:177], v[32:47]
	ds_read_b64_tr_b16 v[178:179], v243 offset:0x600
	ds_read_b64_tr_b16 v[180:181], v243 offset:0xe00
	s_waitcnt lgkmcnt(4)
	v_mfma_f32_32x32x16_bf16 v[32:47], v[216:219], v[162:165], v[32:47]
	ds_read_b64_tr_b16 v[182:183], v243 offset:0x1600
	ds_read_b64_tr_b16 v[184:185], v243 offset:0x1e00
	v_mfma_f32_32x32x16_bf16 v[32:47], v[220:223], v[166:169], v[32:47]
	ds_read_b64_tr_b16 v[216:217], v243 offset:0x2600
	ds_read_b64_tr_b16 v[218:219], v243 offset:0x2e00
	s_waitcnt lgkmcnt(4)
	v_mfma_f32_32x32x16_bf16 v[0:15], v[178:181], v[170:173], v[0:15]
	s_waitcnt lgkmcnt(2)
	v_mfma_f32_32x32x16_bf16 v[0:15], v[182:185], v[174:177], v[0:15]
	s_waitcnt lgkmcnt(0)
	v_mfma_f32_32x32x16_bf16 v[0:15], v[216:219], v[162:165], v[0:15]
	v_mfma_f32_32x32x16_bf16 v[0:15], v[224:227], v[166:169], v[0:15]
	v_sub_f32_e32 v162, v252, v212
	v_cmp_ge_f32_e32 vcc, s91, v162
	s_cmp_eq_u64 vcc, exec
	s_cselect_b64 s[2:3], -1, 0
	v_cndmask_b32_e64 v144, v144, 1.0, s[2:3]
	v_cmp_gt_f32_e32 vcc, 1.0, v144
	s_cbranch_vccz .LBB0_930
	v_pk_mul_f32 v[30:31], v[30:31], v[144:145] op_sel_hi:[1,0]
	v_pk_mul_f32 v[28:29], v[28:29], v[144:145] op_sel_hi:[1,0]
	v_pk_mul_f32 v[26:27], v[26:27], v[144:145] op_sel_hi:[1,0]
	v_pk_mul_f32 v[24:25], v[24:25], v[144:145] op_sel_hi:[1,0]
	v_pk_mul_f32 v[22:23], v[22:23], v[144:145] op_sel_hi:[1,0]
	v_pk_mul_f32 v[20:21], v[20:21], v[144:145] op_sel_hi:[1,0]
	v_pk_mul_f32 v[18:19], v[18:19], v[144:145] op_sel_hi:[1,0]
	v_pk_mul_f32 v[16:17], v[16:17], v[144:145] op_sel_hi:[1,0]
	v_pk_mul_f32 v[62:63], v[62:63], v[144:145] op_sel_hi:[1,0]
	v_pk_mul_f32 v[60:61], v[60:61], v[144:145] op_sel_hi:[1,0]
	v_pk_mul_f32 v[58:59], v[58:59], v[144:145] op_sel_hi:[1,0]
	v_pk_mul_f32 v[56:57], v[56:57], v[144:145] op_sel_hi:[1,0]
	v_pk_mul_f32 v[54:55], v[54:55], v[144:145] op_sel_hi:[1,0]
	v_pk_mul_f32 v[52:53], v[52:53], v[144:145] op_sel_hi:[1,0]
	v_pk_mul_f32 v[50:51], v[50:51], v[144:145] op_sel_hi:[1,0]
	v_pk_mul_f32 v[48:49], v[48:49], v[144:145] op_sel_hi:[1,0]
	v_pk_mul_f32 v[46:47], v[46:47], v[144:145] op_sel_hi:[1,0]
	v_pk_mul_f32 v[44:45], v[44:45], v[144:145] op_sel_hi:[1,0]
	v_pk_mul_f32 v[42:43], v[42:43], v[144:145] op_sel_hi:[1,0]
	v_pk_mul_f32 v[40:41], v[40:41], v[144:145] op_sel_hi:[1,0]
	v_pk_mul_f32 v[38:39], v[38:39], v[144:145] op_sel_hi:[1,0]
	v_pk_mul_f32 v[36:37], v[36:37], v[144:145] op_sel_hi:[1,0]
	v_pk_mul_f32 v[34:35], v[34:35], v[144:145] op_sel_hi:[1,0]
	v_pk_mul_f32 v[32:33], v[32:33], v[144:145] op_sel_hi:[1,0]
	v_pk_mul_f32 v[14:15], v[14:15], v[144:145] op_sel_hi:[1,0]
	v_pk_mul_f32 v[12:13], v[12:13], v[144:145] op_sel_hi:[1,0]
	v_pk_mul_f32 v[10:11], v[10:11], v[144:145] op_sel_hi:[1,0]
	v_pk_mul_f32 v[8:9], v[8:9], v[144:145] op_sel_hi:[1,0]
	v_pk_mul_f32 v[6:7], v[6:7], v[144:145] op_sel_hi:[1,0]
	v_pk_mul_f32 v[4:5], v[4:5], v[144:145] op_sel_hi:[1,0]
	v_pk_mul_f32 v[2:3], v[2:3], v[144:145] op_sel_hi:[1,0]
	v_pk_mul_f32 v[0:1], v[0:1], v[144:145] op_sel_hi:[1,0]
; DI void partialSM(f32x16& p0, f32x16& p1, float& m_reg, float& mn, float& alpha, const float SCALE) {
;     ...
;   float mnC = -mn * C;
; #pragma unroll
;   for (int r = 0; r < 16; ++r) p0[r] = fmaf(p0[r], C, mnC);
; #pragma unroll
;   for (int r = 0; r < 16; ++r) p1[r] = fmaf(p1[r], C, mnC);
; #pragma unroll
;   for (int r = 0; r < 16; ++r) p0[r] = __builtin_amdgcn_exp2f(p0[r]);
; template <int NPE>
; DI void qkt_r(f32x16& p0, f32x16& p1, const char* Ks, const char* Ps, const bf16x8* qr, int r32, int hi) {
;   p0 = f32x16{}; p1 = f32x16{};
; #pragma unroll
;   for (int d0 = 0; d0 < 8; ++d0) { int cb = (d0 * 16 + hi * 8) * 2;
;     bf16x8 b0 = *reinterpret_cast<const bf16x8*>(Ks + KSWZ(r32, cb));
;     bf16x8 b1 = *reinterpret_cast<const bf16x8*>(Ks + KSWZ(32 + r32, cb));
;     p0 = __builtin_amdgcn_mfma_f32_32x32x16_bf16(b0, qr[d0], p0, 0, 0, 0);
;     p1 = __builtin_amdgcn_mfma_f32_32x32x16_bf16(b1, qr[d0], p1, 0, 0, 0); }
; #pragma unroll
;   for (int d0 = 0; d0 < NPE; ++d0) { int cb = (d0 * 16 + hi * 8) * 2;
;     bf16x8 b0 = *reinterpret_cast<const bf16x8*>(Ps + PSWZ(r32, cb));
;     bf16x8 b1 = *reinterpret_cast<const bf16x8*>(Ps + PSWZ(32 + r32, cb));
;     p0 = __builtin_amdgcn_mfma_f32_32x32x16_bf16(b0, qr[8 + d0], p0, 0, 0, 0);
;     p1 = __builtin_amdgcn_mfma_f32_32x32x16_bf16(b1, qr[8 + d0], p1, 0, 0, 0); }
; }
.LBB0_930:
	v_add_u32_e32 v168, s1, v148
	s_add_i32 s30, s1, 0x4000
	v_lshl_add_u64 v[162:163], v[154:155], 0, s[4:5]
	v_readfirstlane_b32 s31, v168
	v_add_u32_e32 v170, s30, v148
	v_lshl_add_u64 v[164:165], v[162:163], 0, s[38:39]
	v_readfirstlane_b32 s30, v170
	s_mov_b32 m0, s31
	s_waitcnt vmcnt(0) lgkmcnt(0)
	v_add_u32_e32 v168, 0x400, v168
	s_barrier
	global_load_lds_dwordx4 v[164:165], off
	v_lshl_add_u64 v[164:165], v[156:157], 0, s[4:5]
	s_mov_b32 m0, s30
	v_readfirstlane_b32 s30, v168
	v_lshl_add_u64 v[166:167], v[164:165], 0, s[40:41]
	v_add_u32_e32 v170, 0x400, v170
	global_load_lds_dwordx4 v[166:167], off
	s_mov_b32 m0, s30
	v_readfirstlane_b32 s30, v170
	v_lshl_add_u64 v[166:167], v[162:163], 0, s[42:43]
	v_add_u32_e32 v243, s62, v191
	global_load_lds_dwordx4 v[166:167], off
	v_lshl_add_u64 v[166:167], v[158:159], 0, s[4:5]
	s_mov_b32 m0, s30
	s_add_i32 s30, s1, 0x8000
	v_lshl_add_u64 v[168:169], v[166:167], 0, s[40:41]
	v_add_u32_e32 v172, s30, v150
	global_load_lds_dwordx4 v[168:169], off
	v_readfirstlane_b32 s30, v172
	v_lshl_add_u64 v[168:169], v[152:153], 0, s[4:5]
	ds_read_b128 v[176:179], v243 offset:24576
	v_lshl_add_u64 v[170:171], v[168:169], 0, s[44:45]
	s_mov_b32 m0, s30
	v_add_u32_e32 v252, s62, v194
	global_load_lds_dwordx4 v[170:171], off
	v_cndmask_b32_e64 v170, v160, v212, s[2:3]
	v_add_u32_e32 v253, s62, v197
	v_mul_f32_e32 v160, 0xbdd53b94, v170
	ds_read_b128 v[244:247], v243 offset:16384
	v_fmamk_f32 v80, v80, 0x3dd53b94, v160
	v_fmamk_f32 v81, v81, 0x3dd53b94, v160
	v_fmamk_f32 v82, v82, 0x3dd53b94, v160
	v_fmamk_f32 v83, v83, 0x3dd53b94, v160
	v_fmamk_f32 v183, v68, 0x3dd53b94, v160
	v_add_u32_e32 v68, s62, v188
	v_exp_f32_e32 v219, v80
	v_exp_f32_e32 v220, v81
	v_exp_f32_e32 v221, v82
	v_exp_f32_e32 v222, v83
	ds_read_b128 v[80:83], v68 offset:24576
	v_fmamk_f32 v84, v84, 0x3dd53b94, v160
	v_fmamk_f32 v85, v85, 0x3dd53b94, v160
	v_fmamk_f32 v86, v86, 0x3dd53b94, v160
	v_fmamk_f32 v87, v87, 0x3dd53b94, v160
	v_fmamk_f32 v88, v88, 0x3dd53b94, v160
	v_fmamk_f32 v89, v89, 0x3dd53b94, v160
	v_fmamk_f32 v90, v90, 0x3dd53b94, v160
	v_fmamk_f32 v91, v91, 0x3dd53b94, v160
	v_fmamk_f32 v92, v92, 0x3dd53b94, v160
	v_fmamk_f32 v93, v93, 0x3dd53b94, v160
	v_fmamk_f32 v94, v94, 0x3dd53b94, v160
	v_fmamk_f32 v95, v95, 0x3dd53b94, v160
	v_exp_f32_e32 v223, v84
	v_exp_f32_e32 v224, v85
	v_exp_f32_e32 v225, v86
	v_exp_f32_e32 v226, v87
	v_exp_f32_e32 v227, v88
	v_exp_f32_e32 v228, v89
	v_exp_f32_e32 v229, v90
	v_exp_f32_e32 v230, v91
	v_exp_f32_e32 v231, v92
	v_exp_f32_e32 v232, v93
	v_exp_f32_e32 v233, v94
	v_exp_f32_e32 v234, v95
	v_fmamk_f32 v171, v64, 0x3dd53b94, v160
	v_fmamk_f32 v180, v65, 0x3dd53b94, v160
	v_fmamk_f32 v181, v66, 0x3dd53b94, v160
	v_fmamk_f32 v182, v67, 0x3dd53b94, v160
	ds_read_b128 v[64:67], v68 offset:16384
	v_fmamk_f32 v184, v69, 0x3dd53b94, v160
	v_fmamk_f32 v185, v70, 0x3dd53b94, v160
	v_fmamk_f32 v186, v71, 0x3dd53b94, v160
	v_fmamk_f32 v212, v72, 0x3dd53b94, v160
	v_fmamk_f32 v215, v73, 0x3dd53b94, v160
	v_fmamk_f32 v216, v74, 0x3dd53b94, v160
	v_fmamk_f32 v217, v75, 0x3dd53b94, v160
	v_fmamk_f32 v218, v76, 0x3dd53b94, v160
	v_fmamk_f32 v235, v77, 0x3dd53b94, v160
	v_fmamk_f32 v236, v78, 0x3dd53b94, v160
	v_fmac_f32_e32 v160, 0x3dd53b94, v79
	v_add_u32_e32 v243, s62, v203
	ds_read_b128 v[248:251], v252 offset:16384
	ds_read_b128 v[172:175], v253 offset:16384
	v_exp_f32_e32 v171, v171
	v_exp_f32_e32 v180, v180
	v_exp_f32_e32 v181, v181
	v_exp_f32_e32 v182, v182
	s_waitcnt lgkmcnt(3)
	v_mfma_f32_32x32x16_bf16 v[80:95], v[80:83], v[136:139], 0
	v_exp_f32_e32 v183, v183
	v_exp_f32_e32 v184, v184
	v_exp_f32_e32 v185, v185
	v_mfma_f32_32x32x16_bf16 v[80:95], v[176:179], v[132:135], v[80:95]
	v_exp_f32_e32 v186, v186
	v_exp_f32_e32 v212, v212
	v_exp_f32_e32 v237, v215
	ds_read_b128 v[176:179], v252 offset:24576
	v_add_u32_e32 v252, s62, v205
	v_exp_f32_e32 v238, v216
	v_exp_f32_e32 v217, v217
	v_exp_f32_e32 v239, v218
	v_exp_f32_e32 v235, v235
	v_exp_f32_e32 v236, v236
	v_exp_f32_e32 v160, v160
	v_cvt_pk_bf16_f32 v218, v212, v237
	s_waitcnt lgkmcnt(3)
	v_mfma_f32_32x32x16_bf16 v[64:79], v[64:67], v[136:139], 0
	v_mfma_f32_32x32x16_bf16 v[64:79], v[244:247], v[132:135], v[64:79]
	s_waitcnt lgkmcnt(2)
	v_mfma_f32_32x32x16_bf16 v[64:79], v[248:251], v[128:131], v[64:79]
	s_waitcnt lgkmcnt(1)
	v_mfma_f32_32x32x16_bf16 v[64:79], v[172:175], v[124:127], v[64:79]
	ds_read_b128 v[248:251], v243 offset:16384
	ds_read_b128 v[172:175], v252 offset:16384
	s_waitcnt lgkmcnt(2)
	v_mfma_f32_32x32x16_bf16 v[80:95], v[176:179], v[128:131], v[80:95]
	ds_read_b128 v[176:179], v253 offset:24576
	v_add_u32_e32 v253, s62, v206
	s_waitcnt lgkmcnt(0)
	v_mfma_f32_32x32x16_bf16 v[80:95], v[176:179], v[124:127], v[80:95]
	v_add_u32_e32 v176, s62, v200
	ds_read_b128 v[244:247], v176 offset:16384
	ds_read_b128 v[176:179], v176 offset:24576
	s_waitcnt lgkmcnt(1)
	v_mfma_f32_32x32x16_bf16 v[64:79], v[244:247], v[120:123], v[64:79]
	s_waitcnt lgkmcnt(0)
	v_mfma_f32_32x32x16_bf16 v[80:95], v[176:179], v[120:123], v[80:95]
	ds_read_b128 v[244:247], v253 offset:16384
	v_mfma_f32_32x32x16_bf16 v[64:79], v[248:251], v[112:115], v[64:79]
	ds_read_b128 v[176:179], v243 offset:24576
	v_add_u32_e32 v243, s62, v208
	v_mfma_f32_32x32x16_bf16 v[64:79], v[172:175], v[108:111], v[64:79]
	ds_read_b128 v[172:175], v243 offset:32768
	s_waitcnt lgkmcnt(2)
	v_mfma_f32_32x32x16_bf16 v[64:79], v[244:247], v[100:103], v[64:79]
	s_waitcnt lgkmcnt(1)
	v_mfma_f32_32x32x16_bf16 v[80:95], v[176:179], v[112:115], v[80:95]
	ds_read_b128 v[176:179], v252 offset:24576
	v_add_u32_e32 v252, s62, v209
	ds_read_b128 v[244:247], v252 offset:32768
	s_waitcnt lgkmcnt(1)
; #define SBAR() __builtin_amdgcn_sched_barrier(0)
; DI void finishSM(f32x16& p0, f32x16& p1, float alpha, float& l_reg, bf16x8& pa0, bf16x8& pa1, bf16x8& pa2, bf16x8& pa3) {
; #pragma unroll
;   for (int r = 0; r < 16; ++r) p1[r] = __builtin_amdgcn_exp2f(p1[r]);
;   float ps = 0;
; #pragma unroll
;   for (int r = 0; r < 16; ++r) ps += p0[r];
; #pragma unroll
;   for (int r = 0; r < 16; ++r) ps += p1[r];
;   { auto rr = __builtin_amdgcn_permlane32_swap(__float_as_uint(ps), __float_as_uint(ps), false, false);
;     ps = __uint_as_float(rr[0]) + __uint_as_float(rr[1]); }
;   l_reg = l_reg * alpha + ps;
;   PK4(p0, 0, pa0); PK4(p0, 8, pa1); PK4(p1, 0, pa2); PK4(p1, 8, pa3);
; }
; template <int D0, bool SPLIT> DI void pv_one(f32x16& od, int vb, bf16x8 pa0, bf16x8 pa1, bf16x8 pa2, bf16x8 pa3) {
;     ...
;   const s16x4 l0 = tr_read<v_rd_off(D0, 0, 0)>(vb), h0 = tr_read<v_rd_off(D0, 0, 1)>(vb), l1 = tr_read<v_rd_off(D0, 1, 0)>(vb), h1 = tr_read<v_rd_off(D0, 1, 1)>(vb);
;   const s16x4 l2 = tr_read<v_rd_off(D0, 2, 0)>(vb), h2 = tr_read<v_rd_off(D0, 2, 1)>(vb), l3 = tr_read<v_rd_off(D0, 3, 0)>(vb), h3 = tr_read<v_rd_off(D0, 3, 1)>(vb);
;   asm volatile("s_waitcnt lgkmcnt(0)" ::: "memory"); SBAR();
;   od = __builtin_amdgcn_mfma_f32_32x32x16_bf16(PKV(l0, h0), pa0, od, 0, 0, 0);
;   od = __builtin_amdgcn_mfma_f32_32x32x16_bf16(PKV(l1, h1), pa1, od, 0, 0, 0);
;   od = __builtin_amdgcn_mfma_f32_32x32x16_bf16(PKV(l2, h2), pa2, od, 0, 0, 0);
;   od = __builtin_amdgcn_mfma_f32_32x32x16_bf16(PKV(l3, h3), pa3, od, 0, 0, 0);
	v_mfma_f32_32x32x16_bf16 v[80:95], v[176:179], v[108:111], v[80:95]
	ds_read_b128 v[176:179], v253 offset:24576
	v_add_u32_e32 v253, s62, v210
	s_waitcnt lgkmcnt(0)
	v_mfma_f32_32x32x16_bf16 v[80:95], v[176:179], v[100:103], v[80:95]
	v_add_u32_e32 v176, s62, v207
	ds_read_b128 v[248:251], v176 offset:32768
	ds_read_b128 v[176:179], v176 offset:36864
	s_waitcnt lgkmcnt(1)
	v_mfma_f32_32x32x16_bf16 v[64:79], v[248:251], v[104:107], v[64:79]
	s_waitcnt lgkmcnt(0)
	v_mfma_f32_32x32x16_bf16 v[80:95], v[176:179], v[104:107], v[80:95]
	ds_read_b128 v[248:251], v253 offset:32768
	v_mfma_f32_32x32x16_bf16 v[64:79], v[172:175], v[140:143], v[64:79]
	ds_read_b128 v[176:179], v243 offset:36864
	v_mfma_f32_32x32x16_bf16 v[64:79], v[244:247], v[96:99], v[64:79]
	v_add_f32_e32 v172, 0, v219
	v_cvt_pk_bf16_f32 v173, v221, v222
	v_add_f32_e32 v172, v220, v172
	v_cvt_pk_bf16_f32 v174, v223, v224
	v_add_f32_e32 v172, v221, v172
	v_cvt_pk_bf16_f32 v221, v236, v160
	v_add_f32_e32 v172, v222, v172
	v_cvt_pk_bf16_f32 v175, v225, v226
	v_add_f32_e32 v172, v223, v172
	v_add_f32_e32 v172, v224, v172
	v_permlane32_swap_b32_e32 v173, v175
	v_add_f32_e32 v172, v225, v172
	v_add_f32_e32 v172, v226, v172
	v_add_f32_e32 v172, v227, v172
	v_add_f32_e32 v172, v228, v172
	v_add_f32_e32 v172, v229, v172
	v_add_f32_e32 v172, v230, v172
	v_add_f32_e32 v172, v231, v172
	v_add_f32_e32 v172, v232, v172
	v_add_f32_e32 v172, v233, v172
	v_add_f32_e32 v172, v234, v172
	v_add_f32_e32 v172, v171, v172
	v_add_f32_e32 v172, v180, v172
	v_cvt_pk_bf16_f32 v180, v171, v180
	v_add_f32_e32 v172, v181, v172
	v_cvt_pk_bf16_f32 v181, v181, v182
	v_add_f32_e32 v172, v182, v172
	v_cvt_pk_bf16_f32 v182, v183, v184
	v_add_f32_e32 v172, v183, v172
	v_cvt_pk_bf16_f32 v183, v185, v186
	v_add_f32_e32 v172, v184, v172
	v_permlane32_swap_b32_e32 v180, v182
	v_add_f32_e32 v172, v185, v172
	v_permlane32_swap_b32_e32 v181, v183
	v_add_f32_e32 v172, v186, v172
	v_add_f32_e32 v172, v212, v172
	s_waitcnt lgkmcnt(1)
	v_mfma_f32_32x32x16_bf16 v[64:79], v[248:251], v[116:119], v[64:79]
	v_add_f32_e32 v172, v237, v172
	v_add_f32_e32 v172, v238, v172
	v_add_f32_e32 v172, v217, v172
	s_waitcnt lgkmcnt(0)
	v_mfma_f32_32x32x16_bf16 v[80:95], v[176:179], v[140:143], v[80:95]
	v_add_f32_e32 v172, v239, v172
	v_add_f32_e32 v172, v235, v172
	v_add_f32_e32 v172, v236, v172
	ds_read_b128 v[176:179], v252 offset:36864
	v_add_f32_e32 v215, v160, v172
	v_add_u32_e32 v160, s63, v147
	v_cvt_pk_bf16_f32 v172, v219, v220
	ds_read_b64_tr_b16 v[222:223], v160 offset:0
	ds_read_b64_tr_b16 v[224:225], v160 offset:0x800
	v_cvt_pk_bf16_f32 v219, v238, v217
	v_permlane32_swap_b32_e32 v172, v174
	v_cvt_pk_bf16_f32 v220, v239, v235
	ds_read_b64_tr_b16 v[236:237], v160 offset:0x3800
	ds_read_b64_tr_b16 v[238:239], v160 offset:0x3200
	ds_read_b64_tr_b16 v[240:241], v160 offset:0x3a00
	v_permlane32_swap_b32_e32 v218, v220
	v_permlane32_swap_b32_e32 v219, v221
	v_max_f32_e32 v171, v64, v64
	v_mov_b32_e32 v216, v215
	s_waitcnt lgkmcnt(5)
	v_mfma_f32_32x32x16_bf16 v[80:95], v[176:179], v[96:99], v[80:95]
	s_waitcnt lgkmcnt(3)
	v_mfma_f32_32x32x16_bf16 v[16:31], v[222:225], v[172:175], v[16:31]
	ds_read_b128 v[176:179], v253 offset:36864
	v_permlane32_swap_b32_e32 v215, v216
	ds_read_b64_tr_b16 v[222:223], v160 offset:0x200
	ds_read_b64_tr_b16 v[224:225], v160 offset:0xa00
	s_waitcnt lgkmcnt(2)
	v_mfma_f32_32x32x16_bf16 v[80:95], v[176:179], v[116:119], v[80:95]
	s_waitcnt lgkmcnt(0)
	v_mfma_f32_32x32x16_bf16 v[48:63], v[222:225], v[172:175], v[48:63]
	v_cvt_pk_bf16_f32 v176, v227, v228
	v_cvt_pk_bf16_f32 v177, v229, v230
	ds_read_b64_tr_b16 v[226:227], v160 offset:0x1000
	ds_read_b64_tr_b16 v[228:229], v160 offset:0x1800
	v_cvt_pk_bf16_f32 v178, v231, v232
	v_cvt_pk_bf16_f32 v179, v233, v234
	ds_read_b64_tr_b16 v[230:231], v160 offset:0x2000
	ds_read_b64_tr_b16 v[232:233], v160 offset:0x2800
	v_permlane32_swap_b32_e32 v176, v178
	v_permlane32_swap_b32_e32 v177, v179
	ds_read_b64_tr_b16 v[222:223], v160 offset:0x400
	ds_read_b64_tr_b16 v[224:225], v160 offset:0xc00
	ds_read_b64_tr_b16 v[234:235], v160 offset:0x3000
	s_waitcnt lgkmcnt(5)
	v_mfma_f32_32x32x16_bf16 v[16:31], v[226:229], v[176:179], v[16:31]
	s_waitcnt lgkmcnt(3)
	v_mfma_f32_32x32x16_bf16 v[16:31], v[230:233], v[180:183], v[16:31]
	ds_read_b64_tr_b16 v[226:227], v160 offset:0x1200
	ds_read_b64_tr_b16 v[228:229], v160 offset:0x1a00
	s_waitcnt lgkmcnt(3)
	v_mfma_f32_32x32x16_bf16 v[32:47], v[222:225], v[172:175], v[32:47]
	ds_read_b64_tr_b16 v[230:231], v160 offset:0x2200
	ds_read_b64_tr_b16 v[232:233], v160 offset:0x2a00
	s_waitcnt lgkmcnt(4)
; #define SBAR() __builtin_amdgcn_sched_barrier(0)
; DI void partialSM(f32x16& p0, f32x16& p1, float& m_reg, float& mn, float& alpha, const float SCALE) {
;   const float C = SCALE * 1.4426950408889634f;
;   float pmax = p0[0];
; #pragma unroll
;   for (int r = 1; r < 16; ++r) pmax = fmaxf(pmax, p0[r]);
; #pragma unroll
;   for (int r = 0; r < 16; ++r) pmax = fmaxf(pmax, p1[r]);
;   { auto rr = __builtin_amdgcn_permlane32_swap(__float_as_uint(pmax), __float_as_uint(pmax), false, false);
;     pmax = fmaxf(__uint_as_float(rr[0]), __uint_as_float(rr[1])); }
;   if (__builtin_expect(__all(pmax - m_reg <= THR / SCALE), 1)) { mn = m_reg; alpha = 1.f; }
;   else { mn = fmaxf(m_reg, pmax); alpha = __builtin_amdgcn_exp2f((m_reg - mn) * C); m_reg = mn; }
; template <int D0, bool SPLIT> DI void pv_one(f32x16& od, int vb, bf16x8 pa0, bf16x8 pa1, bf16x8 pa2, bf16x8 pa3) {
;     ...
;   const s16x4 l0 = tr_read<v_rd_off(D0, 0, 0)>(vb), h0 = tr_read<v_rd_off(D0, 0, 1)>(vb), l1 = tr_read<v_rd_off(D0, 1, 0)>(vb), h1 = tr_read<v_rd_off(D0, 1, 1)>(vb);
;   const s16x4 l2 = tr_read<v_rd_off(D0, 2, 0)>(vb), h2 = tr_read<v_rd_off(D0, 2, 1)>(vb), l3 = tr_read<v_rd_off(D0, 3, 0)>(vb), h3 = tr_read<v_rd_off(D0, 3, 1)>(vb);
;   asm volatile("s_waitcnt lgkmcnt(0)" ::: "memory"); SBAR();
;   od = __builtin_amdgcn_mfma_f32_32x32x16_bf16(PKV(l0, h0), pa0, od, 0, 0, 0);
;   od = __builtin_amdgcn_mfma_f32_32x32x16_bf16(PKV(l1, h1), pa1, od, 0, 0, 0);
;   od = __builtin_amdgcn_mfma_f32_32x32x16_bf16(PKV(l2, h2), pa2, od, 0, 0, 0);
;   od = __builtin_amdgcn_mfma_f32_32x32x16_bf16(PKV(l3, h3), pa3, od, 0, 0, 0);
	v_mfma_f32_32x32x16_bf16 v[16:31], v[234:237], v[218:221], v[16:31]
	ds_read_b64_tr_b16 v[222:223], v160 offset:0x600
	ds_read_b64_tr_b16 v[224:225], v160 offset:0xe00
	ds_read_b64_tr_b16 v[234:235], v160 offset:0x3400
	ds_read_b64_tr_b16 v[236:237], v160 offset:0x3c00
	s_waitcnt lgkmcnt(6)
	v_mfma_f32_32x32x16_bf16 v[48:63], v[226:229], v[176:179], v[48:63]
	s_waitcnt lgkmcnt(4)
	v_mfma_f32_32x32x16_bf16 v[48:63], v[230:233], v[180:183], v[48:63]
	ds_read_b64_tr_b16 v[226:227], v160 offset:0x1400
	ds_read_b64_tr_b16 v[228:229], v160 offset:0x1c00
	v_mfma_f32_32x32x16_bf16 v[48:63], v[238:241], v[218:221], v[48:63]
	ds_read_b64_tr_b16 v[230:231], v160 offset:0x2400
	ds_read_b64_tr_b16 v[232:233], v160 offset:0x2c00
	s_waitcnt lgkmcnt(6)
	v_mfma_f32_32x32x16_bf16 v[0:15], v[222:225], v[172:175], v[0:15]
	ds_read_b64_tr_b16 v[238:239], v160 offset:0x3600
	ds_read_b64_tr_b16 v[240:241], v160 offset:0x3e00
	s_waitcnt lgkmcnt(4)
	v_mfma_f32_32x32x16_bf16 v[32:47], v[226:229], v[176:179], v[32:47]
	s_waitcnt lgkmcnt(2)
	v_mfma_f32_32x32x16_bf16 v[32:47], v[230:233], v[180:183], v[32:47]
	ds_read_b64_tr_b16 v[226:227], v160 offset:0x1600
	ds_read_b64_tr_b16 v[228:229], v160 offset:0x1e00
	v_mfma_f32_32x32x16_bf16 v[32:47], v[234:237], v[218:221], v[32:47]
	ds_read_b64_tr_b16 v[230:231], v160 offset:0x2600
	ds_read_b64_tr_b16 v[232:233], v160 offset:0x2e00
	v_max_f32_e32 v160, v65, v65
	v_max_f32_e32 v160, v171, v160
	v_max3_f32 v160, v160, v66, v67
	v_max3_f32 v160, v160, v68, v69
	v_max3_f32 v160, v160, v70, v71
	v_max3_f32 v160, v160, v72, v73
	v_max3_f32 v160, v160, v74, v75
	v_max3_f32 v160, v160, v76, v77
	v_max3_f32 v160, v160, v78, v79
	v_max3_f32 v160, v160, v80, v81
	v_max3_f32 v160, v160, v82, v83
	v_max3_f32 v160, v160, v84, v85
	v_max3_f32 v160, v160, v86, v87
	v_max3_f32 v160, v160, v88, v89
	v_max3_f32 v160, v160, v90, v91
	v_max3_f32 v160, v160, v92, v93
	v_max3_f32 v160, v160, v94, v95
	v_mov_b32_e32 v171, v160
	s_waitcnt lgkmcnt(2)
	v_mfma_f32_32x32x16_bf16 v[0:15], v[226:229], v[176:179], v[0:15]
	s_waitcnt lgkmcnt(0)
	v_mfma_f32_32x32x16_bf16 v[0:15], v[230:233], v[180:183], v[0:15]
	v_permlane32_swap_b32_e32 v160, v171
	v_max_f32_e32 v171, v171, v171
	v_max_f32_e32 v160, v160, v160
	v_max_f32_e32 v160, v160, v171
	v_mfma_f32_32x32x16_bf16 v[0:15], v[238:241], v[218:221], v[0:15]
	v_max_f32_e32 v171, v170, v170
	v_sub_f32_e32 v172, v160, v170
	v_max_f32_e32 v171, v171, v160
	v_cmp_ge_f32_e32 vcc, s91, v172
	v_sub_f32_e32 v160, v170, v171
	v_mul_f32_e32 v160, 0x3dd53b94, v160
	s_cmp_eq_u64 vcc, exec
	v_exp_f32_e32 v160, v160
	s_cselect_b64 s[2:3], -1, 0
	v_cndmask_b32_e64 v160, v160, 1.0, s[2:3]
	v_cmp_gt_f32_e32 vcc, 1.0, v160
	s_cbranch_vccz .LBB0_932
	v_pk_mul_f32 v[30:31], v[30:31], v[160:161] op_sel_hi:[1,0]
	v_pk_mul_f32 v[28:29], v[28:29], v[160:161] op_sel_hi:[1,0]
	v_pk_mul_f32 v[26:27], v[26:27], v[160:161] op_sel_hi:[1,0]
	v_pk_mul_f32 v[24:25], v[24:25], v[160:161] op_sel_hi:[1,0]
	v_pk_mul_f32 v[22:23], v[22:23], v[160:161] op_sel_hi:[1,0]
	v_pk_mul_f32 v[20:21], v[20:21], v[160:161] op_sel_hi:[1,0]
	v_pk_mul_f32 v[18:19], v[18:19], v[160:161] op_sel_hi:[1,0]
	v_pk_mul_f32 v[16:17], v[16:17], v[160:161] op_sel_hi:[1,0]
	v_pk_mul_f32 v[62:63], v[62:63], v[160:161] op_sel_hi:[1,0]
	v_pk_mul_f32 v[60:61], v[60:61], v[160:161] op_sel_hi:[1,0]
	v_pk_mul_f32 v[58:59], v[58:59], v[160:161] op_sel_hi:[1,0]
	v_pk_mul_f32 v[56:57], v[56:57], v[160:161] op_sel_hi:[1,0]
	v_pk_mul_f32 v[54:55], v[54:55], v[160:161] op_sel_hi:[1,0]
	v_pk_mul_f32 v[52:53], v[52:53], v[160:161] op_sel_hi:[1,0]
	v_pk_mul_f32 v[50:51], v[50:51], v[160:161] op_sel_hi:[1,0]
	v_pk_mul_f32 v[48:49], v[48:49], v[160:161] op_sel_hi:[1,0]
	v_pk_mul_f32 v[46:47], v[46:47], v[160:161] op_sel_hi:[1,0]
	v_pk_mul_f32 v[44:45], v[44:45], v[160:161] op_sel_hi:[1,0]
	v_pk_mul_f32 v[42:43], v[42:43], v[160:161] op_sel_hi:[1,0]
	v_pk_mul_f32 v[40:41], v[40:41], v[160:161] op_sel_hi:[1,0]
	v_pk_mul_f32 v[38:39], v[38:39], v[160:161] op_sel_hi:[1,0]
	v_pk_mul_f32 v[36:37], v[36:37], v[160:161] op_sel_hi:[1,0]
	v_pk_mul_f32 v[34:35], v[34:35], v[160:161] op_sel_hi:[1,0]
	v_pk_mul_f32 v[32:33], v[32:33], v[160:161] op_sel_hi:[1,0]
	v_pk_mul_f32 v[14:15], v[14:15], v[160:161] op_sel_hi:[1,0]
	v_pk_mul_f32 v[12:13], v[12:13], v[160:161] op_sel_hi:[1,0]
	v_pk_mul_f32 v[10:11], v[10:11], v[160:161] op_sel_hi:[1,0]
	v_pk_mul_f32 v[8:9], v[8:9], v[160:161] op_sel_hi:[1,0]
	v_pk_mul_f32 v[6:7], v[6:7], v[160:161] op_sel_hi:[1,0]
	v_pk_mul_f32 v[4:5], v[4:5], v[160:161] op_sel_hi:[1,0]
	v_pk_mul_f32 v[2:3], v[2:3], v[160:161] op_sel_hi:[1,0]
	v_pk_mul_f32 v[0:1], v[0:1], v[160:161] op_sel_hi:[1,0]
